# grid barrier spin loops: s_sleep 1 -> s_sleep 0 (tighter polling, shorter detection delay)
# speedup vs baseline: 1.0250x; 1.0017x over previous
; __global__ void __launch_bounds__(512, 2) fwd_megakernel(Params P) {
;     ...
;     if (ws == nullptr) grid.sync();
.LBB0_11:
	s_sleep 0
	global_load_dword v3, v2, s[6:7] offset:32 sc1
	s_waitcnt vmcnt(0)
	v_and_b32_e32 v3, 0xffff0000, v3
	v_cmp_ne_u32_e32 vcc, v3, v1
	s_or_b64 s[8:9], vcc, s[8:9]
	s_andn2_b64 exec, exec, s[8:9]
	s_cbranch_execnz .LBB0_11

; __device__ __forceinline__ unsigned xb_ld(unsigned* p)              { return __hip_atomic_load(p, __ATOMIC_RELAXED, __HIP_MEMORY_SCOPE_AGENT); }
; __device__ __forceinline__ void xcd_barrier_complete(unsigned* bar, unsigned x, unsigned& nloc, unsigned& nx) {
;     ...
;     for (;;) {
;         sum = 0u; cnt = 0u; mine = 0u;
; #pragma unroll
;         for (unsigned j = 0; j < 16; ++j) { const unsigned c = xb_ld(&bar[XB_XCNT(j)]); sum += c; cnt += (c > 0u) ? 1u : 0u; mine = (j == x) ? c : mine; }
;         if (sum == G) break;
;         __builtin_amdgcn_s_sleep(1);
;         if ((++sp & 255u) == 0u) { if (xb_ld(&bar[XB_TMO])) break; if (sp > XB_SPIN_CAP) { atomicAdd(&bar[XB_TMO], 1u); break; } }
;     }
.LBB0_92:
	global_load_dword v16, v1, s[84:85] offset:1024 sc1
	global_load_dword v0, v1, s[84:85] offset:1280 sc1
	s_waitcnt lgkmcnt(0)
	global_load_dword v2, v1, s[84:85] offset:1536 sc1
	global_load_dword v3, v1, s[84:85] offset:1792 sc1
	global_load_dword v4, v1, s[84:85] offset:2048 sc1
	global_load_dword v5, v1, s[84:85] offset:2304 sc1
	global_load_dword v6, v1, s[84:85] offset:2560 sc1
	global_load_dword v7, v1, s[84:85] offset:2816 sc1
	global_load_dword v8, v1, s[84:85] offset:3072 sc1
	global_load_dword v9, v1, s[84:85] offset:3328 sc1
	global_load_dword v10, v1, s[84:85] offset:3584 sc1
	global_load_dword v11, v1, s[84:85] offset:3840 sc1
	global_load_dword v12, v1, s[48:49] sc1
	global_load_dword v13, v1, s[50:51] sc1
	global_load_dword v14, v1, s[52:53] sc1
	global_load_dword v15, v1, s[54:55] sc1
	s_mov_b64 s[10:11], -1
	s_mov_b64 s[14:15], -1
	s_waitcnt vmcnt(14)
	v_add_u32_e32 v17, v0, v16
	s_waitcnt vmcnt(13)
	v_add_u32_e32 v17, v17, v2
	s_waitcnt vmcnt(12)
	v_add_u32_e32 v17, v17, v3
	s_waitcnt vmcnt(11)
	v_add_u32_e32 v17, v17, v4
	s_waitcnt vmcnt(10)
	v_add_u32_e32 v17, v17, v5
	s_waitcnt vmcnt(9)
	v_add_u32_e32 v17, v17, v6
	s_waitcnt vmcnt(8)
	v_add_u32_e32 v17, v17, v7
	s_waitcnt vmcnt(7)
	v_add_u32_e32 v17, v17, v8
	s_waitcnt vmcnt(6)
	v_add_u32_e32 v17, v17, v9
	s_waitcnt vmcnt(5)
	v_add_u32_e32 v17, v17, v10
	s_waitcnt vmcnt(4)
	v_add_u32_e32 v17, v17, v11
	s_waitcnt vmcnt(3)
	v_add_u32_e32 v17, v17, v12
	s_waitcnt vmcnt(2)
	v_add_u32_e32 v17, v17, v13
	s_waitcnt vmcnt(1)
	v_add_u32_e32 v17, v17, v14
	s_waitcnt vmcnt(0)
	v_add_u32_e32 v17, v17, v15
	v_cmp_eq_u32_e32 vcc, s39, v17
	s_cbranch_vccnz .LBB0_91
	s_and_b32 s5, s4, 0xff
	s_cmp_eq_u32 s5, 0
	s_mov_b64 s[16:17], -1
	s_sleep 0
	s_cbranch_scc0 .LBB0_96
	global_load_dword v17, v1, s[82:83] sc1
	s_waitcnt vmcnt(0)
	v_cmp_eq_u32_e32 vcc, 0, v17
	s_cbranch_vccnz .LBB0_98
	s_mov_b64 s[16:17], 0

.LBB0_110:
	s_and_b32 s5, s4, 0xff
	s_mov_b64 s[22:23], -1
	s_cmp_lg_u32 s5, 0
	s_mov_b64 s[24:25], -1
	s_sleep 0
	s_cbranch_scc1 .LBB0_113
	global_load_dword v2, v1, s[82:83] sc1
	s_waitcnt vmcnt(0)
	v_cmp_eq_u32_e32 vcc, 0, v2
	s_cbranch_vccnz .LBB0_115
	s_mov_b64 s[24:25], 0
	s_mov_b64 s[38:39], -1
